# v103 with 8-byte weight loads (columns interleaved across the two MFMA column blocks: full-line row segments, half the load instructions)
# speedup vs baseline: 1.2090x; 1.0011x over previous
.LBB0_638:
	s_mul_hi_i32 s0, s5, 0x2aaaaaab
	s_lshr_b32 s1, s0, 31
	s_ashr_i32 s6, s0, 5
	s_add_i32 s6, s6, s1
	s_mul_i32 s0, s6, 0xc0
	s_sub_i32 s0, s5, s0
	s_lshl_b32 s2, s0, 5
	v_mov_b32_e32 v32, 0
	s_mul_hi_i32 s7, s6, 0x1800000
	s_mul_i32 s8, s6, 0x1800000
	s_ashr_i32 s3, s2, 31
	v_mov_b32_e32 v15, 0
	v_mov_b32_e32 v14, v32
	v_mov_b32_e32 v17, 0
	v_mov_b32_e32 v16, v32
	v_mov_b32_e32 v19, 0
	v_mov_b32_e32 v18, v32
	v_mov_b32_e32 v21, 0
	v_mov_b32_e32 v20, v32
	v_mov_b32_e32 v12, v3
	s_mov_b64 s[10:11], exec
	s_mov_b64 exec, -1
	v_readfirstlane_b32 s98, v166
	s_lshr_b32 s98, s98, 6
	v_and_b32_e32 v80, 63, v166
	v_and_b32_e32 v81, 15, v80
	v_lshrrev_b32_e32 v82, 4, v80
	s_lshl_b32 s99, s98, 7
	v_lshl_add_u32 v83, v81, 10, v82
	v_add_u32_e32 v83, s99, v83
	v_lshlrev_b32_e32 v83, 2, v83
	v_mov_b32_e32 v86, 0
	v_mov_b32_e32 v87, 0
	v_mov_b32_e32 v88, 0
	v_mov_b32_e32 v89, 0
	v_mov_b32_e32 v90, 0
	v_mov_b32_e32 v91, 0
	v_mov_b32_e32 v92, 0
	v_mov_b32_e32 v93, 0
	v_mov_b32_e32 v117, 0
	v_mov_b32_e32 v118, 0
	v_mov_b32_e32 v119, 0
	v_mov_b32_e32 v120, 0
	v_mov_b32_e32 v121, 0
	v_mov_b32_e32 v122, 0
	v_mov_b32_e32 v123, 0
	v_mov_b32_e32 v124, 0
	v_mov_b32_e32 v125, 0
	v_mov_b32_e32 v126, 0
	v_mov_b32_e32 v127, 0
	v_mov_b32_e32 v128, 0
	v_mov_b32_e32 v129, 0
	v_mov_b32_e32 v130, 0
	v_mov_b32_e32 v131, 0
	v_mov_b32_e32 v132, 0
	v_mov_b32_e32 v133, 0
	v_mov_b32_e32 v134, 0
	v_mov_b32_e32 v135, 0
	v_mov_b32_e32 v136, 0
	v_mov_b32_e32 v137, 0
	v_mov_b32_e32 v138, 0
	v_mov_b32_e32 v139, 0
	v_mov_b32_e32 v140, 0
	v_mov_b32_e32 v141, 0
	v_mov_b32_e32 v142, 0
	v_mov_b32_e32 v143, 0
	v_mov_b32_e32 v144, 0
	v_mov_b32_e32 v145, 0
	v_mov_b32_e32 v146, 0
	v_mov_b32_e32 v147, 0
	v_mov_b32_e32 v148, 0
	v_cmp_gt_u32_e64 s[0:1], 9, v81
	s_nop 1
	s_mov_b64 exec, s[0:1]
	ds_read_b32 v117, v83
	ds_read_b32 v118, v83 offset:16
	ds_read_b32 v119, v83 offset:32
	ds_read_b32 v120, v83 offset:48
	ds_read_b32 v121, v83 offset:64
	ds_read_b32 v122, v83 offset:80
	ds_read_b32 v123, v83 offset:96
	ds_read_b32 v124, v83 offset:112
	ds_read_b32 v125, v83 offset:128
	ds_read_b32 v126, v83 offset:144
	ds_read_b32 v127, v83 offset:160
	ds_read_b32 v128, v83 offset:176
	ds_read_b32 v129, v83 offset:192
	ds_read_b32 v130, v83 offset:208
	ds_read_b32 v131, v83 offset:224
	ds_read_b32 v132, v83 offset:240
	ds_read_b32 v133, v83 offset:256
	ds_read_b32 v134, v83 offset:272
	ds_read_b32 v135, v83 offset:288
	ds_read_b32 v136, v83 offset:304
	ds_read_b32 v137, v83 offset:320
	ds_read_b32 v138, v83 offset:336
	ds_read_b32 v139, v83 offset:352
	ds_read_b32 v140, v83 offset:368
	ds_read_b32 v141, v83 offset:384
	ds_read_b32 v142, v83 offset:400
	ds_read_b32 v143, v83 offset:416
	ds_read_b32 v144, v83 offset:432
	ds_read_b32 v145, v83 offset:448
	ds_read_b32 v146, v83 offset:464
	ds_read_b32 v147, v83 offset:480
	ds_read_b32 v148, v83 offset:496
	s_mov_b64 exec, -1
	s_add_u32 s0, s80, s8
	s_addc_u32 s1, s81, s7
	s_lshl_b32 s9, s2, 2
	s_add_u32 s0, s0, s9
	s_addc_u32 s1, s1, 0
	v_add_u32_e32 v84, s99, v82
	v_mul_u32_u24_e32 v84, 0x1800, v84
	v_lshl_add_u32 v84, v81, 1, v84
	v_lshlrev_b32_e32 v84, 2, v84
	global_load_dwordx2 v[176:177], v84, s[0:1] nt
	s_add_u32 s0, s0, 0x18000
	s_addc_u32 s1, s1, 0
	global_load_dwordx2 v[178:179], v84, s[0:1] nt
	s_add_u32 s0, s0, 0x18000
	s_addc_u32 s1, s1, 0
	global_load_dwordx2 v[180:181], v84, s[0:1] nt
	s_add_u32 s0, s0, 0x18000
	s_addc_u32 s1, s1, 0
	global_load_dwordx2 v[182:183], v84, s[0:1] nt
	s_add_u32 s0, s0, 0x18000
	s_addc_u32 s1, s1, 0
	global_load_dwordx2 v[184:185], v84, s[0:1] nt
	s_add_u32 s0, s0, 0x18000
	s_addc_u32 s1, s1, 0
	global_load_dwordx2 v[186:187], v84, s[0:1] nt
	s_add_u32 s0, s0, 0x18000
	s_addc_u32 s1, s1, 0
	global_load_dwordx2 v[188:189], v84, s[0:1] nt
	s_add_u32 s0, s0, 0x18000
	s_addc_u32 s1, s1, 0
	global_load_dwordx2 v[190:191], v84, s[0:1] nt
	s_add_u32 s0, s0, 0x18000
	s_addc_u32 s1, s1, 0
	global_load_dwordx2 v[192:193], v84, s[0:1] nt
	s_add_u32 s0, s0, 0x18000
	s_addc_u32 s1, s1, 0
	global_load_dwordx2 v[194:195], v84, s[0:1] nt
	s_add_u32 s0, s0, 0x18000
	s_addc_u32 s1, s1, 0
	global_load_dwordx2 v[196:197], v84, s[0:1] nt
	s_add_u32 s0, s0, 0x18000
	s_addc_u32 s1, s1, 0
	global_load_dwordx2 v[198:199], v84, s[0:1] nt
	s_add_u32 s0, s0, 0x18000
	s_addc_u32 s1, s1, 0
	global_load_dwordx2 v[200:201], v84, s[0:1] nt
	s_add_u32 s0, s0, 0x18000
	s_addc_u32 s1, s1, 0
	global_load_dwordx2 v[202:203], v84, s[0:1] nt
	s_add_u32 s0, s0, 0x18000
	s_addc_u32 s1, s1, 0
	global_load_dwordx2 v[204:205], v84, s[0:1] nt
	s_add_u32 s0, s0, 0x18000
	s_addc_u32 s1, s1, 0
	global_load_dwordx2 v[206:207], v84, s[0:1] nt
	s_add_u32 s0, s0, 0x18000
	s_addc_u32 s1, s1, 0
	s_waitcnt lgkmcnt(0)
	s_waitcnt vmcnt(15)
	v_mfma_f32_16x16x4_f32 v[86:89], v117, v176, v[86:89]
	v_mfma_f32_16x16x4_f32 v[90:93], v117, v177, v[90:93]
	global_load_dwordx2 v[208:209], v84, s[0:1] nt
	s_add_u32 s0, s0, 0x18000
	s_addc_u32 s1, s1, 0
	s_waitcnt vmcnt(15)
	v_mfma_f32_16x16x4_f32 v[86:89], v118, v178, v[86:89]
	v_mfma_f32_16x16x4_f32 v[90:93], v118, v179, v[90:93]
	global_load_dwordx2 v[210:211], v84, s[0:1] nt
	s_add_u32 s0, s0, 0x18000
	s_addc_u32 s1, s1, 0
	s_waitcnt vmcnt(15)
	v_mfma_f32_16x16x4_f32 v[86:89], v119, v180, v[86:89]
	v_mfma_f32_16x16x4_f32 v[90:93], v119, v181, v[90:93]
	global_load_dwordx2 v[212:213], v84, s[0:1] nt
	s_add_u32 s0, s0, 0x18000
	s_addc_u32 s1, s1, 0
	s_waitcnt vmcnt(15)
	v_mfma_f32_16x16x4_f32 v[86:89], v120, v182, v[86:89]
	v_mfma_f32_16x16x4_f32 v[90:93], v120, v183, v[90:93]
	global_load_dwordx2 v[234:235], v84, s[0:1] nt
	s_add_u32 s0, s0, 0x18000
	s_addc_u32 s1, s1, 0
	s_waitcnt vmcnt(15)
	v_mfma_f32_16x16x4_f32 v[86:89], v121, v184, v[86:89]
	v_mfma_f32_16x16x4_f32 v[90:93], v121, v185, v[90:93]
	global_load_dwordx2 v[236:237], v84, s[0:1] nt
	s_add_u32 s0, s0, 0x18000
	s_addc_u32 s1, s1, 0
	s_waitcnt vmcnt(15)
	v_mfma_f32_16x16x4_f32 v[86:89], v122, v186, v[86:89]
	v_mfma_f32_16x16x4_f32 v[90:93], v122, v187, v[90:93]
	global_load_dwordx2 v[238:239], v84, s[0:1] nt
	s_add_u32 s0, s0, 0x18000
	s_addc_u32 s1, s1, 0
	s_waitcnt vmcnt(15)
	v_mfma_f32_16x16x4_f32 v[86:89], v123, v188, v[86:89]
	v_mfma_f32_16x16x4_f32 v[90:93], v123, v189, v[90:93]
	global_load_dwordx2 v[240:241], v84, s[0:1] nt
	s_add_u32 s0, s0, 0x18000
	s_addc_u32 s1, s1, 0
	s_waitcnt vmcnt(15)
	v_mfma_f32_16x16x4_f32 v[86:89], v124, v190, v[86:89]
	v_mfma_f32_16x16x4_f32 v[90:93], v124, v191, v[90:93]
	global_load_dwordx2 v[242:243], v84, s[0:1] nt
	s_add_u32 s0, s0, 0x18000
	s_addc_u32 s1, s1, 0
	s_waitcnt vmcnt(15)
	v_mfma_f32_16x16x4_f32 v[86:89], v125, v192, v[86:89]
	v_mfma_f32_16x16x4_f32 v[90:93], v125, v193, v[90:93]
	global_load_dwordx2 v[244:245], v84, s[0:1] nt
	s_add_u32 s0, s0, 0x18000
	s_addc_u32 s1, s1, 0
	s_waitcnt vmcnt(15)
	v_mfma_f32_16x16x4_f32 v[86:89], v126, v194, v[86:89]
	v_mfma_f32_16x16x4_f32 v[90:93], v126, v195, v[90:93]
	global_load_dwordx2 v[246:247], v84, s[0:1] nt
	s_add_u32 s0, s0, 0x18000
	s_addc_u32 s1, s1, 0
	s_waitcnt vmcnt(15)
	v_mfma_f32_16x16x4_f32 v[86:89], v127, v196, v[86:89]
	v_mfma_f32_16x16x4_f32 v[90:93], v127, v197, v[90:93]
	global_load_dwordx2 v[248:249], v84, s[0:1] nt
	s_add_u32 s0, s0, 0x18000
	s_addc_u32 s1, s1, 0
	s_waitcnt vmcnt(15)
	v_mfma_f32_16x16x4_f32 v[86:89], v128, v198, v[86:89]
	v_mfma_f32_16x16x4_f32 v[90:93], v128, v199, v[90:93]
	global_load_dwordx2 v[102:103], v84, s[0:1] nt
	s_add_u32 s0, s0, 0x18000
	s_addc_u32 s1, s1, 0
	s_waitcnt vmcnt(15)
	v_mfma_f32_16x16x4_f32 v[86:89], v129, v200, v[86:89]
	v_mfma_f32_16x16x4_f32 v[90:93], v129, v201, v[90:93]
	global_load_dwordx2 v[104:105], v84, s[0:1] nt
	s_add_u32 s0, s0, 0x18000
	s_addc_u32 s1, s1, 0
	s_waitcnt vmcnt(15)
	v_mfma_f32_16x16x4_f32 v[86:89], v130, v202, v[86:89]
	v_mfma_f32_16x16x4_f32 v[90:93], v130, v203, v[90:93]
	global_load_dwordx2 v[106:107], v84, s[0:1] nt
	s_add_u32 s0, s0, 0x18000
	s_addc_u32 s1, s1, 0
	s_waitcnt vmcnt(15)
	v_mfma_f32_16x16x4_f32 v[86:89], v131, v204, v[86:89]
	v_mfma_f32_16x16x4_f32 v[90:93], v131, v205, v[90:93]
	global_load_dwordx2 v[108:109], v84, s[0:1] nt
	s_add_u32 s0, s0, 0x18000
	s_addc_u32 s1, s1, 0
	s_waitcnt vmcnt(15)
	v_mfma_f32_16x16x4_f32 v[86:89], v132, v206, v[86:89]
	v_mfma_f32_16x16x4_f32 v[90:93], v132, v207, v[90:93]
	global_load_dwordx2 v[110:111], v84, s[0:1] nt
	s_add_u32 s0, s0, 0x18000
	s_addc_u32 s1, s1, 0
	s_waitcnt vmcnt(15)
	v_mfma_f32_16x16x4_f32 v[86:89], v133, v208, v[86:89]
	v_mfma_f32_16x16x4_f32 v[90:93], v133, v209, v[90:93]
	s_waitcnt vmcnt(14)
	v_mfma_f32_16x16x4_f32 v[86:89], v134, v210, v[86:89]
	v_mfma_f32_16x16x4_f32 v[90:93], v134, v211, v[90:93]
	s_waitcnt vmcnt(13)
	v_mfma_f32_16x16x4_f32 v[86:89], v135, v212, v[86:89]
	v_mfma_f32_16x16x4_f32 v[90:93], v135, v213, v[90:93]
	s_waitcnt vmcnt(12)
	v_mfma_f32_16x16x4_f32 v[86:89], v136, v234, v[86:89]
	v_mfma_f32_16x16x4_f32 v[90:93], v136, v235, v[90:93]
	s_waitcnt vmcnt(11)
	v_mfma_f32_16x16x4_f32 v[86:89], v137, v236, v[86:89]
	v_mfma_f32_16x16x4_f32 v[90:93], v137, v237, v[90:93]
	s_waitcnt vmcnt(10)
	v_mfma_f32_16x16x4_f32 v[86:89], v138, v238, v[86:89]
	v_mfma_f32_16x16x4_f32 v[90:93], v138, v239, v[90:93]
	s_waitcnt vmcnt(9)
	v_mfma_f32_16x16x4_f32 v[86:89], v139, v240, v[86:89]
	v_mfma_f32_16x16x4_f32 v[90:93], v139, v241, v[90:93]
	s_waitcnt vmcnt(8)
	v_mfma_f32_16x16x4_f32 v[86:89], v140, v242, v[86:89]
	v_mfma_f32_16x16x4_f32 v[90:93], v140, v243, v[90:93]
	s_waitcnt vmcnt(7)
	v_mfma_f32_16x16x4_f32 v[86:89], v141, v244, v[86:89]
	v_mfma_f32_16x16x4_f32 v[90:93], v141, v245, v[90:93]
	s_waitcnt vmcnt(6)
	v_mfma_f32_16x16x4_f32 v[86:89], v142, v246, v[86:89]
	v_mfma_f32_16x16x4_f32 v[90:93], v142, v247, v[90:93]
	s_waitcnt vmcnt(5)
	v_mfma_f32_16x16x4_f32 v[86:89], v143, v248, v[86:89]
	v_mfma_f32_16x16x4_f32 v[90:93], v143, v249, v[90:93]
	s_waitcnt vmcnt(4)
	v_mfma_f32_16x16x4_f32 v[86:89], v144, v102, v[86:89]
	v_mfma_f32_16x16x4_f32 v[90:93], v144, v103, v[90:93]
	s_waitcnt vmcnt(3)
	v_mfma_f32_16x16x4_f32 v[86:89], v145, v104, v[86:89]
	v_mfma_f32_16x16x4_f32 v[90:93], v145, v105, v[90:93]
	s_waitcnt vmcnt(2)
	v_mfma_f32_16x16x4_f32 v[86:89], v146, v106, v[86:89]
	v_mfma_f32_16x16x4_f32 v[90:93], v146, v107, v[90:93]
	s_waitcnt vmcnt(1)
	v_mfma_f32_16x16x4_f32 v[86:89], v147, v108, v[86:89]
	v_mfma_f32_16x16x4_f32 v[90:93], v147, v109, v[90:93]
	s_waitcnt vmcnt(0)
	v_mfma_f32_16x16x4_f32 v[86:89], v148, v110, v[86:89]
	v_mfma_f32_16x16x4_f32 v[90:93], v148, v111, v[90:93]
	s_mov_b64 exec, s[10:11]
	s_barrier
	s_mov_b64 s[10:11], exec
	s_mov_b64 exec, -1
	s_lshl_b32 s9, s98, 11
	s_add_i32 s9, s9, 0x15900
	v_lshlrev_b32_e32 v85, 9, v82
	v_lshl_add_u32 v85, v81, 3, v85
	v_add_u32_e32 v85, s9, v85
	v_lshl_add_u32 v83, v80, 2, s9
	s_nop 7
	s_nop 7
	ds_write_b32 v85, v86 offset:0
	ds_write_b32 v85, v90 offset:4
	ds_write_b32 v85, v87 offset:128
	ds_write_b32 v85, v91 offset:132
	ds_write_b32 v85, v88 offset:256
	ds_write_b32 v85, v92 offset:260
	ds_write_b32 v85, v89 offset:384
	ds_write_b32 v85, v93 offset:388
	v_mov_b32_e32 v20, 0
	v_mov_b32_e32 v21, 0
	v_mov_b32_e32 v18, 0
	v_mov_b32_e32 v19, 0
	v_mov_b32_e32 v16, 0
	v_mov_b32_e32 v17, 0
	v_mov_b32_e32 v14, 0
	v_mov_b32_e32 v15, 0
	v_mov_b32_e32 v32, 0
	s_waitcnt lgkmcnt(0)
	s_mov_b32 exec_lo, -1
	s_mov_b32 exec_hi, 0
	ds_read_b32 v20, v83
	ds_read_b32 v21, v83 offset:128
	ds_read_b32 v18, v83 offset:256
	ds_read_b32 v19, v83 offset:384
	ds_read_b32 v16, v83 offset:512
	ds_read_b32 v17, v83 offset:640
	ds_read_b32 v14, v83 offset:768
	ds_read_b32 v15, v83 offset:896
	ds_read_b32 v32, v83 offset:1024
	s_waitcnt lgkmcnt(0)
	s_mov_b64 exec, s[10:11]
	ds_write2st64_b32 v31, v20, v21 offset1:1
	ds_write2st64_b32 v31, v18, v19 offset0:2 offset1:3
	ds_write2st64_b32 v31, v16, v17 offset0:4 offset1:5
	ds_write2st64_b32 v31, v14, v15 offset0:6 offset1:7
	ds_write_b32 v31, v32 offset:2048
	s_waitcnt lgkmcnt(0)
	s_barrier
	s_and_saveexec_b64 s[22:23], vcc
	s_cbranch_execz .LBB0_637
	s_mul_i32 s0, s6, 0x1800
	s_add_i32 s0, s0, s2
	v_or_b32_e32 v10, s0, v2
	v_ashrrev_i32_e32 v11, 31, v10
	s_mul_i32 s6, s6, 9
	v_lshl_add_u64 v[10:11], v[10:11], 2, s[82:83]
	v_lshl_add_u64 v[12:13], s[2:3], 2, v[4:5]
	s_mov_b64 s[2:3], 0
	v_mov_b32_e32 v0, v166
